# stage-2 Fourier epilogue: 128 serialized gate load/store round trips batched into 8 counted waits
# speedup vs baseline: 1.0357x; 1.0357x over previous
.LBB0_1152:
	s_and_b64 vcc, exec, s[4:5]
	s_cbranch_vccz .LBB0_1154
	v_readlane_b32 s70, v254, 8
	v_readlane_b32 s71, v254, 9
	v_ashrrev_i32_e32 v0, 1, v144
	s_movk_i32 s0, 0xff80
	v_and_or_b32 v0, v0, s0, v161
	v_lshlrev_b32_e32 v2, 6, v145
	v_and_or_b32 v2, v2, s33, v160
	v_add_u32_e32 v2, s68, v2
	v_lshlrev_b32_e32 v0, 1, v0
	v_mad_u32_u24 v1, v2, s92, v0
	v_lshl_add_u32 v3, v2, 11, v0
	s_mov_b64 s[72:73], s[46:47]
	v_mov_b32_e32 v146, 0
	v_mov_b32_e32 v147, 0
	v_mov_b32_e32 v148, 0
	v_mov_b32_e32 v149, 0
	v_mov_b32_e32 v150, 0
	v_mov_b32_e32 v151, 0
	v_mov_b32_e32 v152, 0
	v_mov_b32_e32 v153, 0
	v_mov_b32_e32 v154, 0
	v_mov_b32_e32 v155, 0
	v_mov_b32_e32 v156, 0
	v_mov_b32_e32 v157, 0
	v_mov_b32_e32 v158, 0
	v_mov_b32_e32 v159, 0
	v_mov_b32_e32 v160, 0
	v_mov_b32_e32 v161, 0
	v_mov_b32_e32 v162, 0
	v_mov_b32_e32 v163, 0
	v_mov_b32_e32 v164, 0
	v_mov_b32_e32 v165, 0
	v_mov_b32_e32 v166, 0
	v_mov_b32_e32 v167, 0
	v_mov_b32_e32 v168, 0
	v_mov_b32_e32 v169, 0
	v_mov_b32_e32 v170, 0
	v_mov_b32_e32 v171, 0
	v_mov_b32_e32 v172, 0
	v_mov_b32_e32 v173, 0
	v_mov_b32_e32 v174, 0
	v_mov_b32_e32 v175, 0
	v_mov_b32_e32 v176, 0
	v_mov_b32_e32 v177, 0
	global_load_short_d16_hi v146, v1, s[70:71]
	global_load_short_d16_hi v147, v1, s[70:71] offset:64
	global_load_short_d16_hi v148, v1, s[70:71] offset:128
	global_load_short_d16_hi v149, v1, s[70:71] offset:192
	s_add_u32 s70, s70, 0x28000
	s_addc_u32 s71, s71, 0
	global_load_short_d16_hi v150, v1, s[70:71]
	global_load_short_d16_hi v151, v1, s[70:71] offset:64
	global_load_short_d16_hi v152, v1, s[70:71] offset:128
	global_load_short_d16_hi v153, v1, s[70:71] offset:192
	s_add_u32 s70, s70, 0x28000
	s_addc_u32 s71, s71, 0
	global_load_short_d16_hi v154, v1, s[70:71]
	global_load_short_d16_hi v155, v1, s[70:71] offset:64
	global_load_short_d16_hi v156, v1, s[70:71] offset:128
	global_load_short_d16_hi v157, v1, s[70:71] offset:192
	s_add_u32 s70, s70, 0x28000
	s_addc_u32 s71, s71, 0
	global_load_short_d16_hi v158, v1, s[70:71]
	global_load_short_d16_hi v159, v1, s[70:71] offset:64
	global_load_short_d16_hi v160, v1, s[70:71] offset:128
	global_load_short_d16_hi v161, v1, s[70:71] offset:192
	s_add_u32 s70, s70, 0xc8000
	s_addc_u32 s71, s71, 0
	global_load_short_d16_hi v162, v1, s[70:71]
	global_load_short_d16_hi v163, v1, s[70:71] offset:64
	global_load_short_d16_hi v164, v1, s[70:71] offset:128
	global_load_short_d16_hi v165, v1, s[70:71] offset:192
	s_add_u32 s70, s70, 0x28000
	s_addc_u32 s71, s71, 0
	global_load_short_d16_hi v166, v1, s[70:71]
	global_load_short_d16_hi v167, v1, s[70:71] offset:64
	global_load_short_d16_hi v168, v1, s[70:71] offset:128
	global_load_short_d16_hi v169, v1, s[70:71] offset:192
	s_add_u32 s70, s70, 0x28000
	s_addc_u32 s71, s71, 0
	global_load_short_d16_hi v170, v1, s[70:71]
	global_load_short_d16_hi v171, v1, s[70:71] offset:64
	global_load_short_d16_hi v172, v1, s[70:71] offset:128
	global_load_short_d16_hi v173, v1, s[70:71] offset:192
	s_add_u32 s70, s70, 0x28000
	s_addc_u32 s71, s71, 0
	global_load_short_d16_hi v174, v1, s[70:71]
	global_load_short_d16_hi v175, v1, s[70:71] offset:64
	global_load_short_d16_hi v176, v1, s[70:71] offset:128
	global_load_short_d16_hi v177, v1, s[70:71] offset:192
	s_add_u32 s70, s70, 0xc8000
	s_addc_u32 s71, s71, 0
	s_waitcnt vmcnt(16)
	v_mul_f32_e32 v178, v118, v146
	v_cvt_pk_bf16_f32 v178, v178, v178
	global_store_short v3, v178, s[72:73]
	v_mul_f32_e32 v179, v86, v147
	v_cvt_pk_bf16_f32 v179, v179, v179
	global_store_short v3, v179, s[72:73] offset:64
	v_mul_f32_e32 v180, v54, v148
	v_cvt_pk_bf16_f32 v180, v180, v180
	global_store_short v3, v180, s[72:73] offset:128
	v_mul_f32_e32 v181, v22, v149
	v_cvt_pk_bf16_f32 v181, v181, v181
	global_store_short v3, v181, s[72:73] offset:192
	s_add_u32 s72, s72, 0x20000
	s_addc_u32 s73, s73, 0
	v_mul_f32_e32 v178, v119, v150
	v_cvt_pk_bf16_f32 v178, v178, v178
	global_store_short v3, v178, s[72:73]
	v_mul_f32_e32 v179, v87, v151
	v_cvt_pk_bf16_f32 v179, v179, v179
	global_store_short v3, v179, s[72:73] offset:64
	v_mul_f32_e32 v180, v55, v152
	v_cvt_pk_bf16_f32 v180, v180, v180
	global_store_short v3, v180, s[72:73] offset:128
	v_mul_f32_e32 v181, v23, v153
	v_cvt_pk_bf16_f32 v181, v181, v181
	global_store_short v3, v181, s[72:73] offset:192
	s_add_u32 s72, s72, 0x20000
	s_addc_u32 s73, s73, 0
	v_mul_f32_e32 v178, v120, v154
	v_cvt_pk_bf16_f32 v178, v178, v178
	global_store_short v3, v178, s[72:73]
	v_mul_f32_e32 v179, v88, v155
	v_cvt_pk_bf16_f32 v179, v179, v179
	global_store_short v3, v179, s[72:73] offset:64
	v_mul_f32_e32 v180, v56, v156
	v_cvt_pk_bf16_f32 v180, v180, v180
	global_store_short v3, v180, s[72:73] offset:128
	v_mul_f32_e32 v181, v24, v157
	v_cvt_pk_bf16_f32 v181, v181, v181
	global_store_short v3, v181, s[72:73] offset:192
	s_add_u32 s72, s72, 0x20000
	s_addc_u32 s73, s73, 0
	v_mul_f32_e32 v178, v121, v158
	v_cvt_pk_bf16_f32 v178, v178, v178
	global_store_short v3, v178, s[72:73]
	v_mul_f32_e32 v179, v89, v159
	v_cvt_pk_bf16_f32 v179, v179, v179
	global_store_short v3, v179, s[72:73] offset:64
	v_mul_f32_e32 v180, v57, v160
	v_cvt_pk_bf16_f32 v180, v180, v180
	global_store_short v3, v180, s[72:73] offset:128
	v_mul_f32_e32 v181, v25, v161
	v_cvt_pk_bf16_f32 v181, v181, v181
	global_store_short v3, v181, s[72:73] offset:192
	s_add_u32 s72, s72, 0xa0000
	s_addc_u32 s73, s73, 0
	global_load_short_d16_hi v146, v1, s[70:71]
	global_load_short_d16_hi v147, v1, s[70:71] offset:64
	global_load_short_d16_hi v148, v1, s[70:71] offset:128
	global_load_short_d16_hi v149, v1, s[70:71] offset:192
	s_add_u32 s70, s70, 0x28000
	s_addc_u32 s71, s71, 0
	global_load_short_d16_hi v150, v1, s[70:71]
	global_load_short_d16_hi v151, v1, s[70:71] offset:64
	global_load_short_d16_hi v152, v1, s[70:71] offset:128
	global_load_short_d16_hi v153, v1, s[70:71] offset:192
	s_add_u32 s70, s70, 0x28000
	s_addc_u32 s71, s71, 0
	global_load_short_d16_hi v154, v1, s[70:71]
	global_load_short_d16_hi v155, v1, s[70:71] offset:64
	global_load_short_d16_hi v156, v1, s[70:71] offset:128
	global_load_short_d16_hi v157, v1, s[70:71] offset:192
	s_add_u32 s70, s70, 0x28000
	s_addc_u32 s71, s71, 0
	global_load_short_d16_hi v158, v1, s[70:71]
	global_load_short_d16_hi v159, v1, s[70:71] offset:64
	global_load_short_d16_hi v160, v1, s[70:71] offset:128
	global_load_short_d16_hi v161, v1, s[70:71] offset:192
	s_add_u32 s70, s70, 0xc8000
	s_addc_u32 s71, s71, 0
	s_waitcnt vmcnt(32)
	v_mul_f32_e32 v178, v122, v162
	v_cvt_pk_bf16_f32 v178, v178, v178
	global_store_short v3, v178, s[72:73]
	v_mul_f32_e32 v179, v90, v163
	v_cvt_pk_bf16_f32 v179, v179, v179
	global_store_short v3, v179, s[72:73] offset:64
	v_mul_f32_e32 v180, v58, v164
	v_cvt_pk_bf16_f32 v180, v180, v180
	global_store_short v3, v180, s[72:73] offset:128
	v_mul_f32_e32 v181, v26, v165
	v_cvt_pk_bf16_f32 v181, v181, v181
	global_store_short v3, v181, s[72:73] offset:192
	s_add_u32 s72, s72, 0x20000
	s_addc_u32 s73, s73, 0
	v_mul_f32_e32 v178, v123, v166
	v_cvt_pk_bf16_f32 v178, v178, v178
	global_store_short v3, v178, s[72:73]
	v_mul_f32_e32 v179, v91, v167
	v_cvt_pk_bf16_f32 v179, v179, v179
	global_store_short v3, v179, s[72:73] offset:64
	v_mul_f32_e32 v180, v59, v168
	v_cvt_pk_bf16_f32 v180, v180, v180
	global_store_short v3, v180, s[72:73] offset:128
	v_mul_f32_e32 v181, v27, v169
	v_cvt_pk_bf16_f32 v181, v181, v181
	global_store_short v3, v181, s[72:73] offset:192
	s_add_u32 s72, s72, 0x20000
	s_addc_u32 s73, s73, 0
	v_mul_f32_e32 v178, v124, v170
	v_cvt_pk_bf16_f32 v178, v178, v178
	global_store_short v3, v178, s[72:73]
	v_mul_f32_e32 v179, v92, v171
	v_cvt_pk_bf16_f32 v179, v179, v179
	global_store_short v3, v179, s[72:73] offset:64
	v_mul_f32_e32 v180, v60, v172
	v_cvt_pk_bf16_f32 v180, v180, v180
	global_store_short v3, v180, s[72:73] offset:128
	v_mul_f32_e32 v181, v28, v173
	v_cvt_pk_bf16_f32 v181, v181, v181
	global_store_short v3, v181, s[72:73] offset:192
	s_add_u32 s72, s72, 0x20000
	s_addc_u32 s73, s73, 0
	v_mul_f32_e32 v178, v125, v174
	v_cvt_pk_bf16_f32 v178, v178, v178
	global_store_short v3, v178, s[72:73]
	v_mul_f32_e32 v179, v93, v175
	v_cvt_pk_bf16_f32 v179, v179, v179
	global_store_short v3, v179, s[72:73] offset:64
	v_mul_f32_e32 v180, v61, v176
	v_cvt_pk_bf16_f32 v180, v180, v180
	global_store_short v3, v180, s[72:73] offset:128
	v_mul_f32_e32 v181, v29, v177
	v_cvt_pk_bf16_f32 v181, v181, v181
	global_store_short v3, v181, s[72:73] offset:192
	s_add_u32 s72, s72, 0xa0000
	s_addc_u32 s73, s73, 0
	global_load_short_d16_hi v162, v1, s[70:71]
	global_load_short_d16_hi v163, v1, s[70:71] offset:64
	global_load_short_d16_hi v164, v1, s[70:71] offset:128
	global_load_short_d16_hi v165, v1, s[70:71] offset:192
	s_add_u32 s70, s70, 0x28000
	s_addc_u32 s71, s71, 0
	global_load_short_d16_hi v166, v1, s[70:71]
	global_load_short_d16_hi v167, v1, s[70:71] offset:64
	global_load_short_d16_hi v168, v1, s[70:71] offset:128
	global_load_short_d16_hi v169, v1, s[70:71] offset:192
	s_add_u32 s70, s70, 0x28000
	s_addc_u32 s71, s71, 0
	global_load_short_d16_hi v170, v1, s[70:71]
	global_load_short_d16_hi v171, v1, s[70:71] offset:64
	global_load_short_d16_hi v172, v1, s[70:71] offset:128
	global_load_short_d16_hi v173, v1, s[70:71] offset:192
	s_add_u32 s70, s70, 0x28000
	s_addc_u32 s71, s71, 0
	global_load_short_d16_hi v174, v1, s[70:71]
	global_load_short_d16_hi v175, v1, s[70:71] offset:64
	global_load_short_d16_hi v176, v1, s[70:71] offset:128
	global_load_short_d16_hi v177, v1, s[70:71] offset:192
	s_add_u32 s70, s70, 0xc8000
	s_addc_u32 s71, s71, 0
	s_waitcnt vmcnt(32)
	v_mul_f32_e32 v178, v126, v146
	v_cvt_pk_bf16_f32 v178, v178, v178
	global_store_short v3, v178, s[72:73]
	v_mul_f32_e32 v179, v94, v147
	v_cvt_pk_bf16_f32 v179, v179, v179
	global_store_short v3, v179, s[72:73] offset:64
	v_mul_f32_e32 v180, v62, v148
	v_cvt_pk_bf16_f32 v180, v180, v180
	global_store_short v3, v180, s[72:73] offset:128
	v_mul_f32_e32 v181, v30, v149
	v_cvt_pk_bf16_f32 v181, v181, v181
	global_store_short v3, v181, s[72:73] offset:192
	s_add_u32 s72, s72, 0x20000
	s_addc_u32 s73, s73, 0
	v_mul_f32_e32 v178, v127, v150
	v_cvt_pk_bf16_f32 v178, v178, v178
	global_store_short v3, v178, s[72:73]
	v_mul_f32_e32 v179, v95, v151
	v_cvt_pk_bf16_f32 v179, v179, v179
	global_store_short v3, v179, s[72:73] offset:64
	v_mul_f32_e32 v180, v63, v152
	v_cvt_pk_bf16_f32 v180, v180, v180
	global_store_short v3, v180, s[72:73] offset:128
	v_mul_f32_e32 v181, v31, v153
	v_cvt_pk_bf16_f32 v181, v181, v181
	global_store_short v3, v181, s[72:73] offset:192
	s_add_u32 s72, s72, 0x20000
	s_addc_u32 s73, s73, 0
	v_mul_f32_e32 v178, v128, v154
	v_cvt_pk_bf16_f32 v178, v178, v178
	global_store_short v3, v178, s[72:73]
	v_mul_f32_e32 v179, v96, v155
	v_cvt_pk_bf16_f32 v179, v179, v179
	global_store_short v3, v179, s[72:73] offset:64
	v_mul_f32_e32 v180, v64, v156
	v_cvt_pk_bf16_f32 v180, v180, v180
	global_store_short v3, v180, s[72:73] offset:128
	v_mul_f32_e32 v181, v32, v157
	v_cvt_pk_bf16_f32 v181, v181, v181
	global_store_short v3, v181, s[72:73] offset:192
	s_add_u32 s72, s72, 0x20000
	s_addc_u32 s73, s73, 0
	v_mul_f32_e32 v178, v129, v158
	v_cvt_pk_bf16_f32 v178, v178, v178
	global_store_short v3, v178, s[72:73]
	v_mul_f32_e32 v179, v97, v159
	v_cvt_pk_bf16_f32 v179, v179, v179
	global_store_short v3, v179, s[72:73] offset:64
	v_mul_f32_e32 v180, v65, v160
	v_cvt_pk_bf16_f32 v180, v180, v180
	global_store_short v3, v180, s[72:73] offset:128
	v_mul_f32_e32 v181, v33, v161
	v_cvt_pk_bf16_f32 v181, v181, v181
	global_store_short v3, v181, s[72:73] offset:192
	s_add_u32 s72, s72, 0xa0000
	s_addc_u32 s73, s73, 0
	global_load_short_d16_hi v146, v1, s[70:71]
	global_load_short_d16_hi v147, v1, s[70:71] offset:64
	global_load_short_d16_hi v148, v1, s[70:71] offset:128
	global_load_short_d16_hi v149, v1, s[70:71] offset:192
	s_add_u32 s70, s70, 0x28000
	s_addc_u32 s71, s71, 0
	global_load_short_d16_hi v150, v1, s[70:71]
	global_load_short_d16_hi v151, v1, s[70:71] offset:64
	global_load_short_d16_hi v152, v1, s[70:71] offset:128
	global_load_short_d16_hi v153, v1, s[70:71] offset:192
	s_add_u32 s70, s70, 0x28000
	s_addc_u32 s71, s71, 0
	global_load_short_d16_hi v154, v1, s[70:71]
	global_load_short_d16_hi v155, v1, s[70:71] offset:64
	global_load_short_d16_hi v156, v1, s[70:71] offset:128
	global_load_short_d16_hi v157, v1, s[70:71] offset:192
	s_add_u32 s70, s70, 0x28000
	s_addc_u32 s71, s71, 0
	global_load_short_d16_hi v158, v1, s[70:71]
	global_load_short_d16_hi v159, v1, s[70:71] offset:64
	global_load_short_d16_hi v160, v1, s[70:71] offset:128
	global_load_short_d16_hi v161, v1, s[70:71] offset:192
	s_add_u32 s70, s70, 0xc8000
	s_addc_u32 s71, s71, 0
	s_waitcnt vmcnt(32)
	v_mul_f32_e32 v178, v130, v162
	v_cvt_pk_bf16_f32 v178, v178, v178
	global_store_short v3, v178, s[72:73]
	v_mul_f32_e32 v179, v98, v163
	v_cvt_pk_bf16_f32 v179, v179, v179
	global_store_short v3, v179, s[72:73] offset:64
	v_mul_f32_e32 v180, v66, v164
	v_cvt_pk_bf16_f32 v180, v180, v180
	global_store_short v3, v180, s[72:73] offset:128
	v_mul_f32_e32 v181, v34, v165
	v_cvt_pk_bf16_f32 v181, v181, v181
	global_store_short v3, v181, s[72:73] offset:192
	s_add_u32 s72, s72, 0x20000
	s_addc_u32 s73, s73, 0
	v_mul_f32_e32 v178, v131, v166
	v_cvt_pk_bf16_f32 v178, v178, v178
	global_store_short v3, v178, s[72:73]
	v_mul_f32_e32 v179, v99, v167
	v_cvt_pk_bf16_f32 v179, v179, v179
	global_store_short v3, v179, s[72:73] offset:64
	v_mul_f32_e32 v180, v67, v168
	v_cvt_pk_bf16_f32 v180, v180, v180
	global_store_short v3, v180, s[72:73] offset:128
	v_mul_f32_e32 v181, v35, v169
	v_cvt_pk_bf16_f32 v181, v181, v181
	global_store_short v3, v181, s[72:73] offset:192
	s_add_u32 s72, s72, 0x20000
	s_addc_u32 s73, s73, 0
	v_mul_f32_e32 v178, v132, v170
	v_cvt_pk_bf16_f32 v178, v178, v178
	global_store_short v3, v178, s[72:73]
	v_mul_f32_e32 v179, v100, v171
	v_cvt_pk_bf16_f32 v179, v179, v179
	global_store_short v3, v179, s[72:73] offset:64
	v_mul_f32_e32 v180, v68, v172
	v_cvt_pk_bf16_f32 v180, v180, v180
	global_store_short v3, v180, s[72:73] offset:128
	v_mul_f32_e32 v181, v36, v173
	v_cvt_pk_bf16_f32 v181, v181, v181
	global_store_short v3, v181, s[72:73] offset:192
	s_add_u32 s72, s72, 0x20000
	s_addc_u32 s73, s73, 0
	v_mul_f32_e32 v178, v133, v174
	v_cvt_pk_bf16_f32 v178, v178, v178
	global_store_short v3, v178, s[72:73]
	v_mul_f32_e32 v179, v101, v175
	v_cvt_pk_bf16_f32 v179, v179, v179
	global_store_short v3, v179, s[72:73] offset:64
	v_mul_f32_e32 v180, v69, v176
	v_cvt_pk_bf16_f32 v180, v180, v180
	global_store_short v3, v180, s[72:73] offset:128
	v_mul_f32_e32 v181, v37, v177
	v_cvt_pk_bf16_f32 v181, v181, v181
	global_store_short v3, v181, s[72:73] offset:192
	s_add_u32 s72, s72, 0xa0000
	s_addc_u32 s73, s73, 0
	global_load_short_d16_hi v162, v1, s[70:71]
	global_load_short_d16_hi v163, v1, s[70:71] offset:64
	global_load_short_d16_hi v164, v1, s[70:71] offset:128
	global_load_short_d16_hi v165, v1, s[70:71] offset:192
	s_add_u32 s70, s70, 0x28000
	s_addc_u32 s71, s71, 0
	global_load_short_d16_hi v166, v1, s[70:71]
	global_load_short_d16_hi v167, v1, s[70:71] offset:64
	global_load_short_d16_hi v168, v1, s[70:71] offset:128
	global_load_short_d16_hi v169, v1, s[70:71] offset:192
	s_add_u32 s70, s70, 0x28000
	s_addc_u32 s71, s71, 0
	global_load_short_d16_hi v170, v1, s[70:71]
	global_load_short_d16_hi v171, v1, s[70:71] offset:64
	global_load_short_d16_hi v172, v1, s[70:71] offset:128
	global_load_short_d16_hi v173, v1, s[70:71] offset:192
	s_add_u32 s70, s70, 0x28000
	s_addc_u32 s71, s71, 0
	global_load_short_d16_hi v174, v1, s[70:71]
	global_load_short_d16_hi v175, v1, s[70:71] offset:64
	global_load_short_d16_hi v176, v1, s[70:71] offset:128
	global_load_short_d16_hi v177, v1, s[70:71] offset:192
	s_add_u32 s70, s70, 0xc8000
	s_addc_u32 s71, s71, 0
	s_waitcnt vmcnt(32)
	v_mul_f32_e32 v178, v102, v146
	v_cvt_pk_bf16_f32 v178, v178, v178
	global_store_short v3, v178, s[72:73]
	v_mul_f32_e32 v179, v70, v147
	v_cvt_pk_bf16_f32 v179, v179, v179
	global_store_short v3, v179, s[72:73] offset:64
	v_mul_f32_e32 v180, v38, v148
	v_cvt_pk_bf16_f32 v180, v180, v180
	global_store_short v3, v180, s[72:73] offset:128
	v_mul_f32_e32 v181, v6, v149
	v_cvt_pk_bf16_f32 v181, v181, v181
	global_store_short v3, v181, s[72:73] offset:192
	s_add_u32 s72, s72, 0x20000
	s_addc_u32 s73, s73, 0
	v_mul_f32_e32 v178, v103, v150
	v_cvt_pk_bf16_f32 v178, v178, v178
	global_store_short v3, v178, s[72:73]
	v_mul_f32_e32 v179, v71, v151
	v_cvt_pk_bf16_f32 v179, v179, v179
	global_store_short v3, v179, s[72:73] offset:64
	v_mul_f32_e32 v180, v39, v152
	v_cvt_pk_bf16_f32 v180, v180, v180
	global_store_short v3, v180, s[72:73] offset:128
	v_mul_f32_e32 v181, v7, v153
	v_cvt_pk_bf16_f32 v181, v181, v181
	global_store_short v3, v181, s[72:73] offset:192
	s_add_u32 s72, s72, 0x20000
	s_addc_u32 s73, s73, 0
	v_mul_f32_e32 v178, v104, v154
	v_cvt_pk_bf16_f32 v178, v178, v178
	global_store_short v3, v178, s[72:73]
	v_mul_f32_e32 v179, v72, v155
	v_cvt_pk_bf16_f32 v179, v179, v179
	global_store_short v3, v179, s[72:73] offset:64
	v_mul_f32_e32 v180, v40, v156
	v_cvt_pk_bf16_f32 v180, v180, v180
	global_store_short v3, v180, s[72:73] offset:128
	v_mul_f32_e32 v181, v8, v157
	v_cvt_pk_bf16_f32 v181, v181, v181
	global_store_short v3, v181, s[72:73] offset:192
	s_add_u32 s72, s72, 0x20000
	s_addc_u32 s73, s73, 0
	v_mul_f32_e32 v178, v105, v158
	v_cvt_pk_bf16_f32 v178, v178, v178
	global_store_short v3, v178, s[72:73]
	v_mul_f32_e32 v179, v73, v159
	v_cvt_pk_bf16_f32 v179, v179, v179
	global_store_short v3, v179, s[72:73] offset:64
	v_mul_f32_e32 v180, v41, v160
	v_cvt_pk_bf16_f32 v180, v180, v180
	global_store_short v3, v180, s[72:73] offset:128
	v_mul_f32_e32 v181, v9, v161
	v_cvt_pk_bf16_f32 v181, v181, v181
	global_store_short v3, v181, s[72:73] offset:192
	s_add_u32 s72, s72, 0xa0000
	s_addc_u32 s73, s73, 0
	global_load_short_d16_hi v146, v1, s[70:71]
	global_load_short_d16_hi v147, v1, s[70:71] offset:64
	global_load_short_d16_hi v148, v1, s[70:71] offset:128
	global_load_short_d16_hi v149, v1, s[70:71] offset:192
	s_add_u32 s70, s70, 0x28000
	s_addc_u32 s71, s71, 0
	global_load_short_d16_hi v150, v1, s[70:71]
	global_load_short_d16_hi v151, v1, s[70:71] offset:64
	global_load_short_d16_hi v152, v1, s[70:71] offset:128
	global_load_short_d16_hi v153, v1, s[70:71] offset:192
	s_add_u32 s70, s70, 0x28000
	s_addc_u32 s71, s71, 0
	global_load_short_d16_hi v154, v1, s[70:71]
	global_load_short_d16_hi v155, v1, s[70:71] offset:64
	global_load_short_d16_hi v156, v1, s[70:71] offset:128
	global_load_short_d16_hi v157, v1, s[70:71] offset:192
	s_add_u32 s70, s70, 0x28000
	s_addc_u32 s71, s71, 0
	global_load_short_d16_hi v158, v1, s[70:71]
	global_load_short_d16_hi v159, v1, s[70:71] offset:64
	global_load_short_d16_hi v160, v1, s[70:71] offset:128
	global_load_short_d16_hi v161, v1, s[70:71] offset:192
	s_add_u32 s70, s70, 0xc8000
	s_addc_u32 s71, s71, 0
	s_waitcnt vmcnt(32)
	v_mul_f32_e32 v178, v106, v162
	v_cvt_pk_bf16_f32 v178, v178, v178
	global_store_short v3, v178, s[72:73]
	v_mul_f32_e32 v179, v74, v163
	v_cvt_pk_bf16_f32 v179, v179, v179
	global_store_short v3, v179, s[72:73] offset:64
	v_mul_f32_e32 v180, v42, v164
	v_cvt_pk_bf16_f32 v180, v180, v180
	global_store_short v3, v180, s[72:73] offset:128
	v_mul_f32_e32 v181, v10, v165
	v_cvt_pk_bf16_f32 v181, v181, v181
	global_store_short v3, v181, s[72:73] offset:192
	s_add_u32 s72, s72, 0x20000
	s_addc_u32 s73, s73, 0
	v_mul_f32_e32 v178, v107, v166
	v_cvt_pk_bf16_f32 v178, v178, v178
	global_store_short v3, v178, s[72:73]
	v_mul_f32_e32 v179, v75, v167
	v_cvt_pk_bf16_f32 v179, v179, v179
	global_store_short v3, v179, s[72:73] offset:64
	v_mul_f32_e32 v180, v43, v168
	v_cvt_pk_bf16_f32 v180, v180, v180
	global_store_short v3, v180, s[72:73] offset:128
	v_mul_f32_e32 v181, v11, v169
	v_cvt_pk_bf16_f32 v181, v181, v181
	global_store_short v3, v181, s[72:73] offset:192
	s_add_u32 s72, s72, 0x20000
	s_addc_u32 s73, s73, 0
	v_mul_f32_e32 v178, v108, v170
	v_cvt_pk_bf16_f32 v178, v178, v178
	global_store_short v3, v178, s[72:73]
	v_mul_f32_e32 v179, v76, v171
	v_cvt_pk_bf16_f32 v179, v179, v179
	global_store_short v3, v179, s[72:73] offset:64
	v_mul_f32_e32 v180, v44, v172
	v_cvt_pk_bf16_f32 v180, v180, v180
	global_store_short v3, v180, s[72:73] offset:128
	v_mul_f32_e32 v181, v12, v173
	v_cvt_pk_bf16_f32 v181, v181, v181
	global_store_short v3, v181, s[72:73] offset:192
	s_add_u32 s72, s72, 0x20000
	s_addc_u32 s73, s73, 0
	v_mul_f32_e32 v178, v109, v174
	v_cvt_pk_bf16_f32 v178, v178, v178
	global_store_short v3, v178, s[72:73]
	v_mul_f32_e32 v179, v77, v175
	v_cvt_pk_bf16_f32 v179, v179, v179
	global_store_short v3, v179, s[72:73] offset:64
	v_mul_f32_e32 v180, v45, v176
	v_cvt_pk_bf16_f32 v180, v180, v180
	global_store_short v3, v180, s[72:73] offset:128
	v_mul_f32_e32 v181, v13, v177
	v_cvt_pk_bf16_f32 v181, v181, v181
	global_store_short v3, v181, s[72:73] offset:192
	s_add_u32 s72, s72, 0xa0000
	s_addc_u32 s73, s73, 0
	global_load_short_d16_hi v162, v1, s[70:71]
	global_load_short_d16_hi v163, v1, s[70:71] offset:64
	global_load_short_d16_hi v164, v1, s[70:71] offset:128
	global_load_short_d16_hi v165, v1, s[70:71] offset:192
	s_add_u32 s70, s70, 0x28000
	s_addc_u32 s71, s71, 0
	global_load_short_d16_hi v166, v1, s[70:71]
	global_load_short_d16_hi v167, v1, s[70:71] offset:64
	global_load_short_d16_hi v168, v1, s[70:71] offset:128
	global_load_short_d16_hi v169, v1, s[70:71] offset:192
	s_add_u32 s70, s70, 0x28000
	s_addc_u32 s71, s71, 0
	global_load_short_d16_hi v170, v1, s[70:71]
	global_load_short_d16_hi v171, v1, s[70:71] offset:64
	global_load_short_d16_hi v172, v1, s[70:71] offset:128
	global_load_short_d16_hi v173, v1, s[70:71] offset:192
	s_add_u32 s70, s70, 0x28000
	s_addc_u32 s71, s71, 0
	global_load_short_d16_hi v174, v1, s[70:71]
	global_load_short_d16_hi v175, v1, s[70:71] offset:64
	global_load_short_d16_hi v176, v1, s[70:71] offset:128
	global_load_short_d16_hi v177, v1, s[70:71] offset:192
	s_waitcnt vmcnt(32)
	v_mul_f32_e32 v178, v110, v146
	v_cvt_pk_bf16_f32 v178, v178, v178
	global_store_short v3, v178, s[72:73]
	v_mul_f32_e32 v179, v78, v147
	v_cvt_pk_bf16_f32 v179, v179, v179
	global_store_short v3, v179, s[72:73] offset:64
	v_mul_f32_e32 v180, v46, v148
	v_cvt_pk_bf16_f32 v180, v180, v180
	global_store_short v3, v180, s[72:73] offset:128
	v_mul_f32_e32 v181, v14, v149
	v_cvt_pk_bf16_f32 v181, v181, v181
	global_store_short v3, v181, s[72:73] offset:192
	s_add_u32 s72, s72, 0x20000
	s_addc_u32 s73, s73, 0
	v_mul_f32_e32 v178, v111, v150
	v_cvt_pk_bf16_f32 v178, v178, v178
	global_store_short v3, v178, s[72:73]
	v_mul_f32_e32 v179, v79, v151
	v_cvt_pk_bf16_f32 v179, v179, v179
	global_store_short v3, v179, s[72:73] offset:64
	v_mul_f32_e32 v180, v47, v152
	v_cvt_pk_bf16_f32 v180, v180, v180
	global_store_short v3, v180, s[72:73] offset:128
	v_mul_f32_e32 v181, v15, v153
	v_cvt_pk_bf16_f32 v181, v181, v181
	global_store_short v3, v181, s[72:73] offset:192
	s_add_u32 s72, s72, 0x20000
	s_addc_u32 s73, s73, 0
	v_mul_f32_e32 v178, v112, v154
	v_cvt_pk_bf16_f32 v178, v178, v178
	global_store_short v3, v178, s[72:73]
	v_mul_f32_e32 v179, v80, v155
	v_cvt_pk_bf16_f32 v179, v179, v179
	global_store_short v3, v179, s[72:73] offset:64
	v_mul_f32_e32 v180, v48, v156
	v_cvt_pk_bf16_f32 v180, v180, v180
	global_store_short v3, v180, s[72:73] offset:128
	v_mul_f32_e32 v181, v16, v157
	v_cvt_pk_bf16_f32 v181, v181, v181
	global_store_short v3, v181, s[72:73] offset:192
	s_add_u32 s72, s72, 0x20000
	s_addc_u32 s73, s73, 0
	v_mul_f32_e32 v178, v113, v158
	v_cvt_pk_bf16_f32 v178, v178, v178
	global_store_short v3, v178, s[72:73]
	v_mul_f32_e32 v179, v81, v159
	v_cvt_pk_bf16_f32 v179, v179, v179
	global_store_short v3, v179, s[72:73] offset:64
	v_mul_f32_e32 v180, v49, v160
	v_cvt_pk_bf16_f32 v180, v180, v180
	global_store_short v3, v180, s[72:73] offset:128
	v_mul_f32_e32 v181, v17, v161
	v_cvt_pk_bf16_f32 v181, v181, v181
	global_store_short v3, v181, s[72:73] offset:192
	s_add_u32 s72, s72, 0xa0000
	s_addc_u32 s73, s73, 0
	s_waitcnt vmcnt(16)
	v_mul_f32_e32 v178, v114, v162
	v_cvt_pk_bf16_f32 v178, v178, v178
	global_store_short v3, v178, s[72:73]
	v_mul_f32_e32 v179, v82, v163
	v_cvt_pk_bf16_f32 v179, v179, v179
	global_store_short v3, v179, s[72:73] offset:64
	v_mul_f32_e32 v180, v50, v164
	v_cvt_pk_bf16_f32 v180, v180, v180
	global_store_short v3, v180, s[72:73] offset:128
	v_mul_f32_e32 v181, v18, v165
	v_cvt_pk_bf16_f32 v181, v181, v181
	global_store_short v3, v181, s[72:73] offset:192
	s_add_u32 s72, s72, 0x20000
	s_addc_u32 s73, s73, 0
	v_mul_f32_e32 v178, v115, v166
	v_cvt_pk_bf16_f32 v178, v178, v178
	global_store_short v3, v178, s[72:73]
	v_mul_f32_e32 v179, v83, v167
	v_cvt_pk_bf16_f32 v179, v179, v179
	global_store_short v3, v179, s[72:73] offset:64
	v_mul_f32_e32 v180, v51, v168
	v_cvt_pk_bf16_f32 v180, v180, v180
	global_store_short v3, v180, s[72:73] offset:128
	v_mul_f32_e32 v181, v19, v169
	v_cvt_pk_bf16_f32 v181, v181, v181
	global_store_short v3, v181, s[72:73] offset:192
	s_add_u32 s72, s72, 0x20000
	s_addc_u32 s73, s73, 0
	v_mul_f32_e32 v178, v116, v170
	v_cvt_pk_bf16_f32 v178, v178, v178
	global_store_short v3, v178, s[72:73]
	v_mul_f32_e32 v179, v84, v171
	v_cvt_pk_bf16_f32 v179, v179, v179
	global_store_short v3, v179, s[72:73] offset:64
	v_mul_f32_e32 v180, v52, v172
	v_cvt_pk_bf16_f32 v180, v180, v180
	global_store_short v3, v180, s[72:73] offset:128
	v_mul_f32_e32 v181, v20, v173
	v_cvt_pk_bf16_f32 v181, v181, v181
	global_store_short v3, v181, s[72:73] offset:192
	s_add_u32 s72, s72, 0x20000
	s_addc_u32 s73, s73, 0
	v_mul_f32_e32 v178, v117, v174
	v_cvt_pk_bf16_f32 v178, v178, v178
	global_store_short v3, v178, s[72:73]
	v_mul_f32_e32 v179, v85, v175
	v_cvt_pk_bf16_f32 v179, v179, v179
	global_store_short v3, v179, s[72:73] offset:64
	v_mul_f32_e32 v180, v53, v176
	v_cvt_pk_bf16_f32 v180, v180, v180
	global_store_short v3, v180, s[72:73] offset:128
	v_mul_f32_e32 v181, v21, v177
	v_cvt_pk_bf16_f32 v181, v181, v181
	global_store_short v3, v181, s[72:73] offset:192
